# comp-0 row-sum with packed adds (stage with few MFMAs); comp-1 keeps scalar adds
# baseline (speedup 1.0000x reference)
.LBB0_711:
	s_cmp_ge_u32 s55, s78
	s_cbranch_scc1 .LBB0_717
	s_and_b32 s55, s50, 0x4000
	v_add_u32_e32 v219, s55, v198
	v_add_u32_e32 v216, v199, v219
	ds_read_b128 v[220:223], v216
	ds_read_b128 v[224:227], v216 offset:8192
	ds_read_b128 v[228:231], v205
	v_xad_u32 v217, v199, 32, v219
	ds_read_b128 v[232:235], v217
	ds_read_b128 v[236:239], v217 offset:8192
	ds_read_b128 v[240:243], v205 offset:32
	v_xad_u32 v216, v199, 64, v219
	ds_read_b128 v[244:247], v216
	ds_read_b128 v[248:251], v216 offset:8192
	ds_read_b128 v[200:203], v205 offset:64
	v_xad_u32 v217, v199, s79, v219
	ds_read_b128 v[208:211], v217
	ds_read_b128 v[212:215], v217 offset:8192
	s_waitcnt lgkmcnt(8)
	v_mfma_f32_32x32x16_bf16 v[162:177], v[220:223], v[228:231], 0
	v_mfma_f32_32x32x16_bf16 v[146:161], v[224:227], v[228:231], 0
	ds_read_b128 v[220:223], v205 offset:96
	s_waitcnt lgkmcnt(6)
	v_mfma_f32_32x32x16_bf16 v[162:177], v[232:235], v[240:243], v[162:177]
	v_mfma_f32_32x32x16_bf16 v[146:161], v[236:239], v[240:243], v[146:161]
	s_waitcnt lgkmcnt(3)
	v_mfma_f32_32x32x16_bf16 v[162:177], v[244:247], v[200:203], v[162:177]
	v_mfma_f32_32x32x16_bf16 v[146:161], v[248:251], v[200:203], v[146:161]
	s_waitcnt lgkmcnt(0)
	v_mfma_f32_32x32x16_bf16 v[162:177], v[208:211], v[220:223], v[162:177]
	v_mfma_f32_32x32x16_bf16 v[146:161], v[212:215], v[220:223], v[146:161]
	v_xad_u32 v254, v199, s80, v219
	ds_read_b128 v[200:203], v254
	ds_read_b128 v[208:211], v254 offset:8192
	ds_read_b128 v[212:215], v205 offset:128
	s_nop 7
	v_fma_f32 v216, v162, s97, -v207
	v_fma_f32 v217, v163, s97, -v207
	v_fma_f32 v252, v164, s97, -v207
	v_fma_f32 v253, v165, s97, -v207
	v_exp_f32_e32 v216, v216
	v_exp_f32_e32 v217, v217
	v_exp_f32_e32 v252, v252
	v_exp_f32_e32 v253, v253
	v_mov_b64_e32 v[16:17], v[216:217]
	v_cvt_pk_bf16_f32 v178, v216, v217
	v_cvt_pk_bf16_f32 v179, v252, v253
	v_pk_add_f32 v[16:17], v[16:17], v[252:253]
	v_fma_f32 v216, v166, s97, -v207
	v_fma_f32 v217, v167, s97, -v207
	v_fma_f32 v252, v168, s97, -v207
	v_fma_f32 v253, v169, s97, -v207
	v_exp_f32_e32 v216, v216
	v_exp_f32_e32 v217, v217
	v_exp_f32_e32 v252, v252
	v_exp_f32_e32 v253, v253
	v_pk_add_f32 v[16:17], v[16:17], v[216:217]
	v_cvt_pk_bf16_f32 v180, v216, v217
	v_cvt_pk_bf16_f32 v181, v252, v253
	v_pk_add_f32 v[16:17], v[16:17], v[252:253]
	s_waitcnt lgkmcnt(0)
	v_mfma_f32_32x32x16_bf16 v[220:235], v[200:203], v[212:215], 0
	v_mfma_f32_32x32x16_bf16 v[236:251], v[208:211], v[212:215], 0
	v_xad_u32 v204, v199, s81, v219
	ds_read_b128 v[200:203], v204
	ds_read_b128 v[208:211], v204 offset:8192
	ds_read_b128 v[212:215], v205 offset:160
	v_fma_f32 v216, v170, s97, -v207
	v_fma_f32 v217, v171, s97, -v207
	v_fma_f32 v252, v172, s97, -v207
	v_fma_f32 v253, v173, s97, -v207
	v_exp_f32_e32 v216, v216
	v_exp_f32_e32 v217, v217
	v_exp_f32_e32 v252, v252
	v_exp_f32_e32 v253, v253
	v_pk_add_f32 v[16:17], v[16:17], v[216:217]
	v_cvt_pk_bf16_f32 v12, v216, v217
	v_cvt_pk_bf16_f32 v13, v252, v253
	v_pk_add_f32 v[16:17], v[16:17], v[252:253]
	v_fma_f32 v216, v174, s97, -v207
	v_fma_f32 v217, v175, s97, -v207
	v_fma_f32 v252, v176, s97, -v207
	v_fma_f32 v253, v177, s97, -v207
	v_exp_f32_e32 v216, v216
	v_exp_f32_e32 v217, v217
	v_exp_f32_e32 v252, v252
	v_exp_f32_e32 v253, v253
	v_pk_add_f32 v[16:17], v[16:17], v[216:217]
	v_cvt_pk_bf16_f32 v14, v216, v217
	v_cvt_pk_bf16_f32 v15, v252, v253
	v_pk_add_f32 v[16:17], v[16:17], v[252:253]
	s_waitcnt lgkmcnt(0)
	v_mfma_f32_32x32x16_bf16 v[220:235], v[200:203], v[212:215], v[220:235]
	v_mfma_f32_32x32x16_bf16 v[236:251], v[208:211], v[212:215], v[236:251]
	v_xad_u32 v254, v199, s82, v219
	ds_read_b128 v[200:203], v254
	ds_read_b128 v[208:211], v254 offset:8192
	ds_read_b128 v[212:215], v205 offset:192
	v_fma_f32 v216, v146, s97, -v207
	v_fma_f32 v217, v147, s97, -v207
	v_fma_f32 v252, v148, s97, -v207
	v_fma_f32 v253, v149, s97, -v207
	v_exp_f32_e32 v216, v216
	v_exp_f32_e32 v217, v217
	v_exp_f32_e32 v252, v252
	v_exp_f32_e32 v253, v253
	v_pk_add_f32 v[16:17], v[16:17], v[216:217]
	v_cvt_pk_bf16_f32 v8, v216, v217
	v_cvt_pk_bf16_f32 v9, v252, v253
	v_pk_add_f32 v[16:17], v[16:17], v[252:253]
	v_fma_f32 v216, v150, s97, -v207
	v_fma_f32 v217, v151, s97, -v207
	v_fma_f32 v252, v152, s97, -v207
	v_fma_f32 v253, v153, s97, -v207
	v_exp_f32_e32 v216, v216
	v_exp_f32_e32 v217, v217
	v_exp_f32_e32 v252, v252
	v_exp_f32_e32 v253, v253
	v_pk_add_f32 v[16:17], v[16:17], v[216:217]
	v_cvt_pk_bf16_f32 v10, v216, v217
	v_cvt_pk_bf16_f32 v11, v252, v253
	v_pk_add_f32 v[16:17], v[16:17], v[252:253]
	s_waitcnt lgkmcnt(0)
	v_mfma_f32_32x32x16_bf16 v[220:235], v[200:203], v[212:215], v[220:235]
	v_mfma_f32_32x32x16_bf16 v[236:251], v[208:211], v[212:215], v[236:251]
	v_xad_u32 v204, v199, s83, v219
	ds_read_b128 v[200:203], v204
	ds_read_b128 v[208:211], v204 offset:8192
	ds_read_b128 v[212:215], v205 offset:224
	v_fma_f32 v216, v154, s97, -v207
	v_fma_f32 v217, v155, s97, -v207
	v_fma_f32 v252, v156, s97, -v207
	v_fma_f32 v253, v157, s97, -v207
	v_exp_f32_e32 v216, v216
	v_exp_f32_e32 v217, v217
	v_exp_f32_e32 v252, v252
	v_exp_f32_e32 v253, v253
	v_pk_add_f32 v[16:17], v[16:17], v[216:217]
	v_cvt_pk_bf16_f32 v4, v216, v217
	v_cvt_pk_bf16_f32 v5, v252, v253
	v_pk_add_f32 v[16:17], v[16:17], v[252:253]
	v_fma_f32 v216, v158, s97, -v207
	v_fma_f32 v217, v159, s97, -v207
	v_fma_f32 v252, v160, s97, -v207
	v_fma_f32 v253, v161, s97, -v207
	v_exp_f32_e32 v216, v216
	v_exp_f32_e32 v217, v217
	v_exp_f32_e32 v252, v252
	v_exp_f32_e32 v253, v253
	v_pk_add_f32 v[16:17], v[16:17], v[216:217]
	v_cvt_pk_bf16_f32 v6, v216, v217
	v_cvt_pk_bf16_f32 v7, v252, v253
	v_pk_add_f32 v[16:17], v[16:17], v[252:253]
	s_waitcnt lgkmcnt(0)
	v_mfma_f32_32x32x16_bf16 v[220:235], v[200:203], v[212:215], v[220:235]
	v_mfma_f32_32x32x16_bf16 v[236:251], v[208:211], v[212:215], v[236:251]
	v_add_f32_e32 v16, v16, v17
	v_mov_b32_e32 v17, 0x43800000
	v_cmp_lt_f32_e32 vcc, v17, v16
	s_cmp_lg_u64 vcc, 0
	s_cbranch_scc0 .Lat_ok0
	v_max3_f32 v16, v162, v163, v164
	v_max3_f32 v17, v146, v147, v148
	v_max3_f32 v16, v16, v165, v166
	v_max3_f32 v17, v17, v149, v150
	v_max3_f32 v16, v16, v167, v168
	v_max3_f32 v17, v17, v151, v152
	v_max3_f32 v16, v16, v169, v170
	v_max3_f32 v17, v17, v153, v154
	v_max3_f32 v16, v16, v171, v172
	v_max3_f32 v17, v17, v155, v156
	v_max3_f32 v16, v16, v173, v174
	v_max3_f32 v17, v17, v157, v158
	v_max3_f32 v16, v16, v175, v176
	v_max3_f32 v17, v17, v159, v160
	v_max_f32_e32 v17, v17, v161
	v_max3_f32 v16, v16, v177, v17
	v_mov_b32_e32 v17, v16
	s_nop 1
	v_permlane32_swap_b32_e32 v16, v17
	v_max_f32_e32 v16, v16, v17
	v_mul_f32_e32 v16, s97, v16
	v_max_f32_e32 v17, v207, v16
	v_sub_f32_e32 v216, v207, v17
	v_exp_f32_e32 v216, v216
	v_mov_b32_e32 v207, v17
	s_nop 0
	v_pk_mul_f32 v[144:145], v[144:145], v[216:217] op_sel_hi:[1,0]
	v_pk_mul_f32 v[142:143], v[142:143], v[216:217] op_sel_hi:[1,0]
	v_pk_mul_f32 v[140:141], v[140:141], v[216:217] op_sel_hi:[1,0]
	v_pk_mul_f32 v[138:139], v[138:139], v[216:217] op_sel_hi:[1,0]
	v_pk_mul_f32 v[136:137], v[136:137], v[216:217] op_sel_hi:[1,0]
	v_pk_mul_f32 v[134:135], v[134:135], v[216:217] op_sel_hi:[1,0]
	v_pk_mul_f32 v[132:133], v[132:133], v[216:217] op_sel_hi:[1,0]
	v_pk_mul_f32 v[130:131], v[130:131], v[216:217] op_sel_hi:[1,0]
	v_pk_mul_f32 v[112:113], v[112:113], v[216:217] op_sel_hi:[1,0]
	v_pk_mul_f32 v[110:111], v[110:111], v[216:217] op_sel_hi:[1,0]
	v_pk_mul_f32 v[108:109], v[108:109], v[216:217] op_sel_hi:[1,0]
	v_pk_mul_f32 v[106:107], v[106:107], v[216:217] op_sel_hi:[1,0]
	v_pk_mul_f32 v[104:105], v[104:105], v[216:217] op_sel_hi:[1,0]
	v_pk_mul_f32 v[102:103], v[102:103], v[216:217] op_sel_hi:[1,0]
	v_pk_mul_f32 v[100:101], v[100:101], v[216:217] op_sel_hi:[1,0]
	v_pk_mul_f32 v[98:99], v[98:99], v[216:217] op_sel_hi:[1,0]
	v_pk_mul_f32 v[80:81], v[80:81], v[216:217] op_sel_hi:[1,0]
	v_pk_mul_f32 v[78:79], v[78:79], v[216:217] op_sel_hi:[1,0]
	v_pk_mul_f32 v[76:77], v[76:77], v[216:217] op_sel_hi:[1,0]
	v_pk_mul_f32 v[74:75], v[74:75], v[216:217] op_sel_hi:[1,0]
	v_pk_mul_f32 v[72:73], v[72:73], v[216:217] op_sel_hi:[1,0]
	v_pk_mul_f32 v[70:71], v[70:71], v[216:217] op_sel_hi:[1,0]
	v_pk_mul_f32 v[68:69], v[68:69], v[216:217] op_sel_hi:[1,0]
	v_pk_mul_f32 v[66:67], v[66:67], v[216:217] op_sel_hi:[1,0]
	v_pk_mul_f32 v[48:49], v[48:49], v[216:217] op_sel_hi:[1,0]
	v_pk_mul_f32 v[46:47], v[46:47], v[216:217] op_sel_hi:[1,0]
	v_pk_mul_f32 v[44:45], v[44:45], v[216:217] op_sel_hi:[1,0]
	v_pk_mul_f32 v[42:43], v[42:43], v[216:217] op_sel_hi:[1,0]
	v_pk_mul_f32 v[40:41], v[40:41], v[216:217] op_sel_hi:[1,0]
	v_pk_mul_f32 v[38:39], v[38:39], v[216:217] op_sel_hi:[1,0]
	v_pk_mul_f32 v[36:37], v[36:37], v[216:217] op_sel_hi:[1,0]
	v_pk_mul_f32 v[34:35], v[34:35], v[216:217] op_sel_hi:[1,0]
	v_mul_f32_e32 v186, v186, v216
	v_fma_f32 v216, v162, s97, -v207
	v_fma_f32 v217, v163, s97, -v207
	v_fma_f32 v252, v164, s97, -v207
	v_fma_f32 v253, v165, s97, -v207
	v_exp_f32_e32 v216, v216
	v_exp_f32_e32 v217, v217
	v_exp_f32_e32 v252, v252
	v_exp_f32_e32 v253, v253
	v_mov_b64_e32 v[16:17], v[216:217]
	v_cvt_pk_bf16_f32 v178, v216, v217
	v_cvt_pk_bf16_f32 v179, v252, v253
	v_pk_add_f32 v[16:17], v[16:17], v[252:253]
	v_fma_f32 v216, v166, s97, -v207
	v_fma_f32 v217, v167, s97, -v207
	v_fma_f32 v252, v168, s97, -v207
	v_fma_f32 v253, v169, s97, -v207
	v_exp_f32_e32 v216, v216
	v_exp_f32_e32 v217, v217
	v_exp_f32_e32 v252, v252
	v_exp_f32_e32 v253, v253
	v_pk_add_f32 v[16:17], v[16:17], v[216:217]
	v_cvt_pk_bf16_f32 v180, v216, v217
	v_cvt_pk_bf16_f32 v181, v252, v253
	v_pk_add_f32 v[16:17], v[16:17], v[252:253]
	v_fma_f32 v216, v170, s97, -v207
	v_fma_f32 v217, v171, s97, -v207
	v_fma_f32 v252, v172, s97, -v207
	v_fma_f32 v253, v173, s97, -v207
	v_exp_f32_e32 v216, v216
	v_exp_f32_e32 v217, v217
	v_exp_f32_e32 v252, v252
	v_exp_f32_e32 v253, v253
	v_pk_add_f32 v[16:17], v[16:17], v[216:217]
	v_cvt_pk_bf16_f32 v12, v216, v217
	v_cvt_pk_bf16_f32 v13, v252, v253
	v_pk_add_f32 v[16:17], v[16:17], v[252:253]
	v_fma_f32 v216, v174, s97, -v207
	v_fma_f32 v217, v175, s97, -v207
	v_fma_f32 v252, v176, s97, -v207
	v_fma_f32 v253, v177, s97, -v207
	v_exp_f32_e32 v216, v216
	v_exp_f32_e32 v217, v217
	v_exp_f32_e32 v252, v252
	v_exp_f32_e32 v253, v253
	v_pk_add_f32 v[16:17], v[16:17], v[216:217]
	v_cvt_pk_bf16_f32 v14, v216, v217
	v_cvt_pk_bf16_f32 v15, v252, v253
	v_pk_add_f32 v[16:17], v[16:17], v[252:253]
	v_fma_f32 v216, v146, s97, -v207
	v_fma_f32 v217, v147, s97, -v207
	v_fma_f32 v252, v148, s97, -v207
	v_fma_f32 v253, v149, s97, -v207
	v_exp_f32_e32 v216, v216
	v_exp_f32_e32 v217, v217
	v_exp_f32_e32 v252, v252
	v_exp_f32_e32 v253, v253
	v_pk_add_f32 v[16:17], v[16:17], v[216:217]
	v_cvt_pk_bf16_f32 v8, v216, v217
	v_cvt_pk_bf16_f32 v9, v252, v253
	v_pk_add_f32 v[16:17], v[16:17], v[252:253]
	v_fma_f32 v216, v150, s97, -v207
	v_fma_f32 v217, v151, s97, -v207
	v_fma_f32 v252, v152, s97, -v207
	v_fma_f32 v253, v153, s97, -v207
	v_exp_f32_e32 v216, v216
	v_exp_f32_e32 v217, v217
	v_exp_f32_e32 v252, v252
	v_exp_f32_e32 v253, v253
	v_pk_add_f32 v[16:17], v[16:17], v[216:217]
	v_cvt_pk_bf16_f32 v10, v216, v217
	v_cvt_pk_bf16_f32 v11, v252, v253
	v_pk_add_f32 v[16:17], v[16:17], v[252:253]
	v_fma_f32 v216, v154, s97, -v207
	v_fma_f32 v217, v155, s97, -v207
	v_fma_f32 v252, v156, s97, -v207
	v_fma_f32 v253, v157, s97, -v207
	v_exp_f32_e32 v216, v216
	v_exp_f32_e32 v217, v217
	v_exp_f32_e32 v252, v252
	v_exp_f32_e32 v253, v253
	v_pk_add_f32 v[16:17], v[16:17], v[216:217]
	v_cvt_pk_bf16_f32 v4, v216, v217
	v_cvt_pk_bf16_f32 v5, v252, v253
	v_pk_add_f32 v[16:17], v[16:17], v[252:253]
	v_fma_f32 v216, v158, s97, -v207
	v_fma_f32 v217, v159, s97, -v207
	v_fma_f32 v252, v160, s97, -v207
	v_fma_f32 v253, v161, s97, -v207
	v_exp_f32_e32 v216, v216
	v_exp_f32_e32 v217, v217
	v_exp_f32_e32 v252, v252
	v_exp_f32_e32 v253, v253
	v_pk_add_f32 v[16:17], v[16:17], v[216:217]
	v_cvt_pk_bf16_f32 v6, v216, v217
	v_cvt_pk_bf16_f32 v7, v252, v253
	v_pk_add_f32 v[16:17], v[16:17], v[252:253]
	v_add_f32_e32 v16, v16, v17
; DI void attn_item(const Params& p, char* smem, u16* qbase, const u16* gabase, const u16* kbase, const u16* vtbase,
;                   int tkv, int nkt, int mylimit, const float* lam_p, const int g_wave) {
;     ...
; #pragma unroll
;       for (int d = 0; d < 4; ++d) {
;         const int vrow = 32 * d + r;
; #pragma unroll
;         for (int sp = 0; sp < 4; ++sp) {
;           const u32x2 lo = *(const u32x2*)(Vt + vrow * 128 + ((32 * sp) ^ vz) + 8 * hh);
;           const u32x2 hi = *(const u32x2*)(Vt + vrow * 128 + ((32 * sp + 16) ^ vz) + 8 * hh);
;           u32x4 w = {lo[0], lo[1], hi[0], hi[1]};
;           const bf16x8 vf = *reinterpret_cast<bf16x8*>(&w);
;           O0[d] = __builtin_amdgcn_mfma_f32_32x32x16_bf16(vf, pf0[sp], O0[d], 0, 0, 0);
;           O1[d] = __builtin_amdgcn_mfma_f32_32x32x16_bf16(vf, pf1[sp], O1[d], 0, 0, 0);
;         }
.Lat_ok0:
	v_add_f32_e32 v186, v186, v16
	v_add_u32_e32 v219, s55, v206
	v_add_u32_e32 v200, v182, v219
	v_xad_u32 v201, v182, 32, v219
	v_xad_u32 v202, v182, 64, v219
	v_xad_u32 v203, v182, s79, v219
	ds_read_b128 v[162:165], v200 offset:32768
	ds_read_b128 v[166:169], v200 offset:36864
	ds_read_b128 v[170:173], v200 offset:40960
	ds_read_b128 v[174:177], v200 offset:45056
	v_max3_f32 v16, v220, v221, v222
	v_max3_f32 v17, v236, v237, v238
	v_max3_f32 v16, v16, v223, v224
	v_max3_f32 v17, v17, v239, v240
	v_max3_f32 v16, v16, v225, v226
	v_max3_f32 v17, v17, v241, v242
	v_max3_f32 v16, v16, v227, v228
	v_max3_f32 v17, v17, v243, v244
	s_waitcnt lgkmcnt(3)
	v_mfma_f32_32x32x16_bf16 v[130:145], v[162:165], v[178:181], v[130:145]
	v_max3_f32 v16, v16, v229, v230
	v_max3_f32 v17, v17, v245, v246
	v_max3_f32 v16, v16, v231, v232
	v_max3_f32 v17, v17, v247, v248
	v_max3_f32 v16, v16, v233, v234
	v_max3_f32 v17, v17, v249, v250
	v_max_f32_e32 v17, v17, v251
	v_max3_f32 v16, v16, v235, v17
	s_waitcnt lgkmcnt(2)
	v_mfma_f32_32x32x16_bf16 v[98:113], v[166:169], v[178:181], v[98:113]
	v_mov_b32_e32 v17, v16
	s_nop 1
	v_permlane32_swap_b32_e32 v16, v17
	v_max_f32_e32 v16, v16, v17
	v_mul_f32_e32 v16, s97, v16
	v_add_f32_e32 v17, 0x41000000, v2
	v_cmp_le_f32_e32 vcc, v16, v17
	s_cmp_eq_u64 vcc, exec
	s_cbranch_scc1 .Lat_nr1
	v_max_f32_e32 v17, v2, v16
	v_sub_f32_e32 v216, v2, v17
	v_exp_f32_e32 v216, v216
	v_mov_b32_e32 v2, v17
	s_nop 0
	v_pk_mul_f32 v[128:129], v[128:129], v[216:217] op_sel_hi:[1,0]
	v_pk_mul_f32 v[126:127], v[126:127], v[216:217] op_sel_hi:[1,0]
	v_pk_mul_f32 v[124:125], v[124:125], v[216:217] op_sel_hi:[1,0]
	v_pk_mul_f32 v[122:123], v[122:123], v[216:217] op_sel_hi:[1,0]
	v_pk_mul_f32 v[120:121], v[120:121], v[216:217] op_sel_hi:[1,0]
	v_pk_mul_f32 v[118:119], v[118:119], v[216:217] op_sel_hi:[1,0]
	v_pk_mul_f32 v[116:117], v[116:117], v[216:217] op_sel_hi:[1,0]
	v_pk_mul_f32 v[114:115], v[114:115], v[216:217] op_sel_hi:[1,0]
	v_pk_mul_f32 v[96:97], v[96:97], v[216:217] op_sel_hi:[1,0]
	v_pk_mul_f32 v[94:95], v[94:95], v[216:217] op_sel_hi:[1,0]
	v_pk_mul_f32 v[92:93], v[92:93], v[216:217] op_sel_hi:[1,0]
	v_pk_mul_f32 v[90:91], v[90:91], v[216:217] op_sel_hi:[1,0]
	v_pk_mul_f32 v[88:89], v[88:89], v[216:217] op_sel_hi:[1,0]
	v_pk_mul_f32 v[86:87], v[86:87], v[216:217] op_sel_hi:[1,0]
	v_pk_mul_f32 v[84:85], v[84:85], v[216:217] op_sel_hi:[1,0]
	v_pk_mul_f32 v[82:83], v[82:83], v[216:217] op_sel_hi:[1,0]
	v_pk_mul_f32 v[64:65], v[64:65], v[216:217] op_sel_hi:[1,0]
	v_pk_mul_f32 v[62:63], v[62:63], v[216:217] op_sel_hi:[1,0]
	v_pk_mul_f32 v[60:61], v[60:61], v[216:217] op_sel_hi:[1,0]
	v_pk_mul_f32 v[58:59], v[58:59], v[216:217] op_sel_hi:[1,0]
	v_pk_mul_f32 v[56:57], v[56:57], v[216:217] op_sel_hi:[1,0]
	v_pk_mul_f32 v[54:55], v[54:55], v[216:217] op_sel_hi:[1,0]
	v_pk_mul_f32 v[52:53], v[52:53], v[216:217] op_sel_hi:[1,0]
	v_pk_mul_f32 v[50:51], v[50:51], v[216:217] op_sel_hi:[1,0]
	v_pk_mul_f32 v[32:33], v[32:33], v[216:217] op_sel_hi:[1,0]
	v_pk_mul_f32 v[30:31], v[30:31], v[216:217] op_sel_hi:[1,0]
	v_pk_mul_f32 v[28:29], v[28:29], v[216:217] op_sel_hi:[1,0]
	v_pk_mul_f32 v[26:27], v[26:27], v[216:217] op_sel_hi:[1,0]
	v_pk_mul_f32 v[24:25], v[24:25], v[216:217] op_sel_hi:[1,0]
	v_pk_mul_f32 v[22:23], v[22:23], v[216:217] op_sel_hi:[1,0]
	v_pk_mul_f32 v[20:21], v[20:21], v[216:217] op_sel_hi:[1,0]
	v_pk_mul_f32 v[18:19], v[18:19], v[216:217] op_sel_hi:[1,0]
	v_mul_f32_e32 v187, v187, v216
; DI void attn_item(const Params& p, char* smem, u16* qbase, const u16* gabase, const u16* kbase, const u16* vtbase,
;                   int tkv, int nkt, int mylimit, const float* lam_p, const int g_wave) {
;     ...
; #pragma unroll
;       for (int d = 0; d < 4; ++d) {
;         const int vrow = 32 * d + r;
; #pragma unroll
;         for (int sp = 0; sp < 4; ++sp) {
;           const u32x2 lo = *(const u32x2*)(Vt + vrow * 128 + ((32 * sp) ^ vz) + 8 * hh);
;           const u32x2 hi = *(const u32x2*)(Vt + vrow * 128 + ((32 * sp + 16) ^ vz) + 8 * hh);
;           u32x4 w = {lo[0], lo[1], hi[0], hi[1]};
;           const bf16x8 vf = *reinterpret_cast<bf16x8*>(&w);
;           O0[d] = __builtin_amdgcn_mfma_f32_32x32x16_bf16(vf, pf0[sp], O0[d], 0, 0, 0);
;           O1[d] = __builtin_amdgcn_mfma_f32_32x32x16_bf16(vf, pf1[sp], O1[d], 0, 0, 0);
;         }
.Lat_nr1:
	s_waitcnt lgkmcnt(1)
	v_mfma_f32_32x32x16_bf16 v[66:81], v[170:173], v[178:181], v[66:81]
	v_fma_f32 v220, v220, s97, -v2
	v_fma_f32 v221, v221, s97, -v2
	v_fma_f32 v222, v222, s97, -v2
	v_fma_f32 v223, v223, s97, -v2
	v_fma_f32 v224, v224, s97, -v2
	v_fma_f32 v225, v225, s97, -v2
	v_fma_f32 v226, v226, s97, -v2
	v_fma_f32 v227, v227, s97, -v2
	s_waitcnt lgkmcnt(0)
	v_mfma_f32_32x32x16_bf16 v[34:49], v[174:177], v[178:181], v[34:49]
	v_exp_f32_e32 v220, v220
	v_exp_f32_e32 v221, v221
	v_exp_f32_e32 v222, v222
	v_exp_f32_e32 v223, v223
	v_exp_f32_e32 v224, v224
	v_exp_f32_e32 v225, v225
	v_exp_f32_e32 v226, v226
	v_exp_f32_e32 v227, v227
	v_fma_f32 v228, v228, s97, -v2
	v_fma_f32 v229, v229, s97, -v2
	v_fma_f32 v230, v230, s97, -v2
	v_fma_f32 v231, v231, s97, -v2
	v_fma_f32 v232, v232, s97, -v2
	v_fma_f32 v233, v233, s97, -v2
	v_fma_f32 v234, v234, s97, -v2
	v_fma_f32 v235, v235, s97, -v2
	v_cvt_pk_bf16_f32 v146, v220, v221
	v_cvt_pk_bf16_f32 v147, v222, v223
	v_cvt_pk_bf16_f32 v148, v224, v225
	v_cvt_pk_bf16_f32 v149, v226, v227
	s_nop 1
	v_mfma_f32_32x32x16_bf16 v[114:129], v[162:165], v[146:149], v[114:129]
	ds_read_b128 v[162:165], v201 offset:32768
	v_exp_f32_e32 v228, v228
	v_exp_f32_e32 v229, v229
	v_exp_f32_e32 v230, v230
	v_exp_f32_e32 v231, v231
	v_exp_f32_e32 v232, v232
	v_exp_f32_e32 v233, v233
	v_exp_f32_e32 v234, v234
	v_mfma_f32_32x32x16_bf16 v[82:97], v[166:169], v[146:149], v[82:97]
	ds_read_b128 v[166:169], v201 offset:36864
	v_exp_f32_e32 v235, v235
	v_mov_b32_e32 v16, v220
	v_mov_b32_e32 v17, v221
	v_add_f32_e32 v16, v222, v16
	v_add_f32_e32 v17, v223, v17
	v_add_f32_e32 v16, v224, v16
	v_add_f32_e32 v17, v225, v17
	v_mfma_f32_32x32x16_bf16 v[50:65], v[170:173], v[146:149], v[50:65]
	ds_read_b128 v[170:173], v201 offset:40960
	v_add_f32_e32 v16, v226, v16
	v_add_f32_e32 v17, v227, v17
	v_cvt_pk_bf16_f32 v150, v228, v229
	v_cvt_pk_bf16_f32 v151, v230, v231
	v_cvt_pk_bf16_f32 v152, v232, v233
	v_cvt_pk_bf16_f32 v153, v234, v235
	v_fma_f32 v236, v236, s97, -v2
	v_mfma_f32_32x32x16_bf16 v[18:33], v[174:177], v[146:149], v[18:33]
	ds_read_b128 v[174:177], v201 offset:45056
	v_fma_f32 v237, v237, s97, -v2
	v_fma_f32 v238, v238, s97, -v2
	v_fma_f32 v239, v239, s97, -v2
	v_fma_f32 v240, v240, s97, -v2
	v_fma_f32 v241, v241, s97, -v2
	v_fma_f32 v242, v242, s97, -v2
	v_fma_f32 v243, v243, s97, -v2
	s_waitcnt lgkmcnt(3)
	v_mfma_f32_32x32x16_bf16 v[130:145], v[162:165], v[12:15], v[130:145]
	v_mfma_f32_32x32x16_bf16 v[114:129], v[162:165], v[150:153], v[114:129]
	ds_read_b128 v[162:165], v202 offset:32768
	v_exp_f32_e32 v236, v236
	v_exp_f32_e32 v237, v237
	v_exp_f32_e32 v238, v238
	v_exp_f32_e32 v239, v239
	v_exp_f32_e32 v240, v240
	v_exp_f32_e32 v241, v241
	v_exp_f32_e32 v242, v242
	s_waitcnt lgkmcnt(3)
	v_mfma_f32_32x32x16_bf16 v[98:113], v[166:169], v[12:15], v[98:113]
	v_mfma_f32_32x32x16_bf16 v[82:97], v[166:169], v[150:153], v[82:97]
	ds_read_b128 v[166:169], v202 offset:36864
	v_exp_f32_e32 v243, v243
	v_add_f32_e32 v16, v228, v16
	v_add_f32_e32 v17, v229, v17
	v_add_f32_e32 v16, v230, v16
	v_add_f32_e32 v17, v231, v17
	v_add_f32_e32 v16, v232, v16
	v_add_f32_e32 v17, v233, v17
	s_waitcnt lgkmcnt(3)
	v_mfma_f32_32x32x16_bf16 v[66:81], v[170:173], v[12:15], v[66:81]
	v_mfma_f32_32x32x16_bf16 v[50:65], v[170:173], v[150:153], v[50:65]
	ds_read_b128 v[170:173], v202 offset:40960
	v_add_f32_e32 v16, v234, v16
	v_add_f32_e32 v17, v235, v17
	v_cvt_pk_bf16_f32 v154, v236, v237
	v_cvt_pk_bf16_f32 v155, v238, v239
	v_cvt_pk_bf16_f32 v156, v240, v241
	v_cvt_pk_bf16_f32 v157, v242, v243
	v_fma_f32 v244, v244, s97, -v2
	s_waitcnt lgkmcnt(3)
	v_mfma_f32_32x32x16_bf16 v[34:49], v[174:177], v[12:15], v[34:49]
	v_mfma_f32_32x32x16_bf16 v[18:33], v[174:177], v[150:153], v[18:33]
	ds_read_b128 v[174:177], v202 offset:45056
	v_fma_f32 v245, v245, s97, -v2
	v_fma_f32 v246, v246, s97, -v2
	v_fma_f32 v247, v247, s97, -v2
	v_fma_f32 v248, v248, s97, -v2
	v_fma_f32 v249, v249, s97, -v2
	v_fma_f32 v250, v250, s97, -v2
	v_fma_f32 v251, v251, s97, -v2
	s_waitcnt lgkmcnt(3)
	v_mfma_f32_32x32x16_bf16 v[130:145], v[162:165], v[8:11], v[130:145]
	v_mfma_f32_32x32x16_bf16 v[114:129], v[162:165], v[154:157], v[114:129]
	ds_read_b128 v[162:165], v203 offset:32768
	v_exp_f32_e32 v244, v244
	v_exp_f32_e32 v245, v245
	v_exp_f32_e32 v246, v246
	v_exp_f32_e32 v247, v247
	v_exp_f32_e32 v248, v248
	v_exp_f32_e32 v249, v249
	v_exp_f32_e32 v250, v250
	s_waitcnt lgkmcnt(3)
	v_mfma_f32_32x32x16_bf16 v[98:113], v[166:169], v[8:11], v[98:113]
	v_mfma_f32_32x32x16_bf16 v[82:97], v[166:169], v[154:157], v[82:97]
	ds_read_b128 v[166:169], v203 offset:36864
	v_exp_f32_e32 v251, v251
	v_add_f32_e32 v16, v236, v16
	v_add_f32_e32 v17, v237, v17
	v_add_f32_e32 v16, v238, v16
	v_add_f32_e32 v17, v239, v17
	v_add_f32_e32 v16, v240, v16
	v_add_f32_e32 v17, v241, v17
	s_waitcnt lgkmcnt(3)
	v_mfma_f32_32x32x16_bf16 v[66:81], v[170:173], v[8:11], v[66:81]
	v_mfma_f32_32x32x16_bf16 v[50:65], v[170:173], v[154:157], v[50:65]
	ds_read_b128 v[170:173], v203 offset:40960
	v_add_f32_e32 v16, v242, v16
	v_add_f32_e32 v17, v243, v17
	v_cvt_pk_bf16_f32 v158, v244, v245
	v_cvt_pk_bf16_f32 v159, v246, v247
	v_cvt_pk_bf16_f32 v160, v248, v249
	v_cvt_pk_bf16_f32 v161, v250, v251
	v_add_f32_e32 v16, v244, v16
	s_waitcnt lgkmcnt(3)
	v_mfma_f32_32x32x16_bf16 v[34:49], v[174:177], v[8:11], v[34:49]
	v_mfma_f32_32x32x16_bf16 v[18:33], v[174:177], v[154:157], v[18:33]
	ds_read_b128 v[174:177], v203 offset:45056
	v_add_f32_e32 v17, v245, v17
	v_add_f32_e32 v16, v246, v16
	v_add_f32_e32 v17, v247, v17
	v_add_f32_e32 v16, v248, v16
	v_add_f32_e32 v17, v249, v17
	v_add_f32_e32 v16, v250, v16
	v_add_f32_e32 v17, v251, v17
	s_waitcnt lgkmcnt(3)
	v_mfma_f32_32x32x16_bf16 v[130:145], v[162:165], v[4:7], v[130:145]
	v_mfma_f32_32x32x16_bf16 v[114:129], v[162:165], v[158:161], v[114:129]
	v_add_f32_e32 v16, v16, v17
	s_waitcnt lgkmcnt(2)
	v_mfma_f32_32x32x16_bf16 v[98:113], v[166:169], v[4:7], v[98:113]
	v_mfma_f32_32x32x16_bf16 v[82:97], v[166:169], v[158:161], v[82:97]
	v_add_f32_e32 v187, v187, v16
	s_waitcnt lgkmcnt(1)
	v_mfma_f32_32x32x16_bf16 v[66:81], v[170:173], v[4:7], v[66:81]
	v_mfma_f32_32x32x16_bf16 v[50:65], v[170:173], v[158:161], v[50:65]
	s_waitcnt lgkmcnt(0)
	v_mfma_f32_32x32x16_bf16 v[34:49], v[174:177], v[4:7], v[34:49]
	v_mfma_f32_32x32x16_bf16 v[18:33], v[174:177], v[158:161], v[18:33]
